# ragged-round overlap: every workgroup arrives at seam 1 as soon as its P2-visible tiles are stored (workgroups 0..63 before their 12th tile, without waiting), all wait for the release only right befor
# baseline (speedup 1.0000x reference)
; __device__ __forceinline__ void own_barrier(unsigned* cnt, unsigned G) {
;     asm volatile("s_waitcnt vmcnt(0) lgkmcnt(0)" ::: "memory");
;     __syncthreads();
;     if (threadIdx.x == 0) {
;         __builtin_amdgcn_fence(__ATOMIC_RELEASE, "agent"); asm volatile("s_waitcnt vmcnt(0)" ::: "memory");
;         unsigned target;
;         if ((G & 7u) == 0u) { target = 8u;
;             const unsigned old = __hip_atomic_fetch_add(cnt + 64 * (1 + (blockIdx.x & 7)), 1u, __ATOMIC_RELAXED, __HIP_MEMORY_SCOPE_AGENT);
;             if (old + 1u == (G >> 3)) __hip_atomic_fetch_add(cnt, 1u, __ATOMIC_RELAXED, __HIP_MEMORY_SCOPE_AGENT); }
;         else { target = G; __hip_atomic_fetch_add(cnt, 1u, __ATOMIC_RELAXED, __HIP_MEMORY_SCOPE_AGENT); }
;         unsigned spins = 0;
;         while (__hip_atomic_load(cnt, __ATOMIC_RELAXED, __HIP_MEMORY_SCOPE_AGENT) < target && ++spins < (1u << 22)) __builtin_amdgcn_s_sleep(1);
;         __builtin_amdgcn_fence(__ATOMIC_ACQUIRE, "agent"); asm volatile("s_waitcnt vmcnt(0)" ::: "memory");
.Lmid_wait:
	s_mov_b64 exec, -1
	s_branch .Lmid_join
	s_mov_b32 s100, 0x400000

; __device__ __forceinline__ void own_barrier(unsigned* cnt, unsigned G) {
;     asm volatile("s_waitcnt vmcnt(0) lgkmcnt(0)" ::: "memory");
;     __syncthreads();
;     if (threadIdx.x == 0) {
;         __builtin_amdgcn_fence(__ATOMIC_RELEASE, "agent"); asm volatile("s_waitcnt vmcnt(0)" ::: "memory");
;         unsigned target;
;         if ((G & 7u) == 0u) { target = 8u;
;             const unsigned old = __hip_atomic_fetch_add(cnt + 64 * (1 + (blockIdx.x & 7)), 1u, __ATOMIC_RELAXED, __HIP_MEMORY_SCOPE_AGENT);
;             if (old + 1u == (G >> 3)) __hip_atomic_fetch_add(cnt, 1u, __ATOMIC_RELAXED, __HIP_MEMORY_SCOPE_AGENT); }
;         else { target = G; __hip_atomic_fetch_add(cnt, 1u, __ATOMIC_RELAXED, __HIP_MEMORY_SCOPE_AGENT); }
;         unsigned spins = 0;
;         while (__hip_atomic_load(cnt, __ATOMIC_RELAXED, __HIP_MEMORY_SCOPE_AGENT) < target && ++spins < (1u << 22)) __builtin_amdgcn_s_sleep(1);
;         __builtin_amdgcn_fence(__ATOMIC_ACQUIRE, "agent"); asm volatile("s_waitcnt vmcnt(0)" ::: "memory");
;     }
;     __syncthreads();
; }
.LBB0_279:
	s_waitcnt vmcnt(0) lgkmcnt(0)
	v_cmp_eq_u32_e64 s[0:1], 0, v160
	v_cmp_ne_u32_e32 vcc, 0, v160
	s_waitcnt vmcnt(0)
	v_writelane_b32 v242, s0, 4
	s_barrier
	s_nop 0
	v_writelane_b32 v242, s1, 5
	s_and_saveexec_b64 s[0:1], vcc
	s_xor_b64 s[0:1], exec, s[0:1]
	s_and_b32 s4, s92, 7
	s_or_saveexec_b64 s[0:1], s[0:1]
	v_mov_b32_e32 v0, s4
	s_xor_b64 exec, exec, s[0:1]
	s_cbranch_execz .LBB0_301
	s_cmp_lg_u32 s101, 1
	s_cbranch_scc1 .Lseam1_go
.Lseam1_pollonly:
	s_lshl_b32 s100, s2, 12
	s_add_u32 s100, s100, 0x8e10000
	v_mov_b32_e32 v1, s100
	s_branch .Lseam1_wait
